# final seam for row-groups complete after tile round 2 runs in phase 14's idle third round (completion counter + writeback), rest in phase 15
# baseline (speedup 1.0000x reference)
.LBB0_1144:
	s_add_i32 s41, s41, 1
	s_cmp_eq_u32 s41, 3
	s_cbranch_scc0 .Lp14_nosig
	s_waitcnt vmcnt(0)
	s_barrier
	s_cmp_eq_u32 s3, 0x100
	s_cbranch_scc0 .Lp14_nosig
	s_mov_b64 s[0:1], exec
	s_mov_b64 exec, 1
	buffer_wbl2 sc1
	s_waitcnt vmcnt(0)
	s_add_u32 s6, s34, 0x321e100
	s_addc_u32 s7, s35, 0
	v_mov_b32_e32 v0, 0
	v_mov_b32_e32 v1, 1
	global_atomic_add v0, v1, s[6:7]
	s_mov_b64 exec, s[0:1]
.Lp14_nosig:
	s_mul_i32 s0, s41, s45
	s_mul_hi_u32 s1, s41, s46
	s_add_i32 s1, s1, s0
	s_mul_i32 s0, s41, s46
	s_add_u32 s8, s0, s2
	s_addc_u32 s9, s1, s42
	v_cmp_gt_i64_e64 s[6:7], s[8:9], v[142:143]
	v_cmp_lt_i64_e64 s[0:1], s[8:9], v[140:141]
	s_and_b64 vcc, exec, s[6:7]
	s_cbranch_vccnz .LBB0_1146
	s_mul_i32 s29, s9, 0x66666667
	s_mul_hi_u32 s55, s8, 0x66666667
	s_mul_hi_u32 s28, s9, 0x66666667
	s_add_u32 s29, s29, s55
	s_mul_i32 s25, s8, 0x66666666
	s_addc_u32 s28, s28, 0
	s_mul_hi_u32 s24, s8, 0x66666666
	s_add_u32 s25, s25, s29
	s_addc_u32 s24, s24, 0
	s_add_u32 s24, s28, s24
	s_addc_u32 s25, 0, 0
	s_mul_i32 s29, s9, 0x66666666
	s_mul_hi_u32 s28, s9, 0x66666666
	s_add_u32 s24, s29, s24
	s_addc_u32 s25, s28, s25
	s_ashr_i32 s9, s9, 31
	s_mul_i32 s28, s9, 0x66666666
	s_mul_hi_u32 s29, s9, 0x66666667
	s_add_i32 s28, s29, s28
	s_mul_i32 s9, s9, 0x66666667
	s_add_i32 s28, s28, s9
	s_add_u32 s24, s24, s9
	s_addc_u32 s25, s25, s28
	s_lshr_b32 s9, s25, 31
	s_lshr_b64 s[24:25], s[24:25], 8
	s_add_i32 s55, s24, s9
	s_mul_i32 s9, s55, 0x280
	s_sub_i32 s8, s8, s9
	s_sext_i32_i16 s9, s8
	s_bfe_u32 s9, s9, 0x3001c
	s_add_i32 s9, s8, s9
	s_sext_i32_i16 s24, s9
	s_and_b32 s9, s9, 0xfff8
	s_sub_i32 s8, s8, s9
	s_ashr_i32 s24, s24, 3
	s_sext_i32_i16 s9, s8
	s_cmp_lt_i32 s9, 0
	s_cselect_b32 s9, s27, 0x50
	s_mul_i32 s8, s9, s8
	s_add_i32 s8, s8, s24
	s_sext_i32_i16 s9, s8
	s_bfe_u32 s9, s9, 0x5001a
	s_add_i32 s9, s8, s9
	s_sext_i32_i16 s24, s9
	s_and_b32 s9, s9, 0xffe0
	s_sub_i32 s8, s8, s9
	s_bfe_i32 s9, s8, 0x80000
	s_bfe_u32 s9, s9, 0x3000c
	s_add_i32 s9, s8, s9
	s_bfe_i32 s25, s9, 0x80000
	s_and_b32 s9, s9, 0xf8
	s_ashr_i32 s24, s24, 5
	s_sub_i32 s8, s8, s9
	s_lshl_b32 s24, s24, 3
	s_sext_i32_i16 s25, s25
	s_sext_i32_i8 s8, s8
	s_add_i32 s60, s24, s8
	s_ashr_i32 s57, s25, 3

.LBB0_1156:
	s_waitcnt vmcnt(0)
	s_lshr_b32 s0, s3, 6
	s_lshl_b32 s1, s2, 3
	s_add_i32 s1, s1, s0
	s_lshr_b32 s4, s1, 8
	s_lshr_b32 s5, s4, 1
	s_mul_i32 s5, s5, 5
	s_and_b32 s4, s4, 1
	s_lshl_b32 s4, s4, 1
	s_add_i32 s5, s5, s4
	s_add_i32 s5, s5, 2
	s_lshl_b32 s5, s5, 11
	s_and_b32 s4, s1, 255
	s_lshl_b32 s4, s4, 3
	s_add_i32 s5, s5, s4
	v_mov_b32_e32 v120, s5
	s_mov_b32 s10, -1
	s_mov_b32 s12, -1
	s_mov_b32 s11, 0
	s_mov_b32 s13, 0
	s_cmp_lt_u32 s2, 128
	s_cbranch_scc1 .Lp14_norange
	s_sub_i32 s4, s2, 128
	s_lshl_b32 s4, s4, 3
	s_add_i32 s4, s4, s0
	s_mul_i32 s4, s4, 24
	s_lshr_b32 s5, s4, 11
	s_and_b32 s6, s4, 2047
	s_mul_i32 s7, s5, 11
	s_lshr_b32 s7, s7, 5
	s_mul_i32 s8, s7, 3
	s_sub_i32 s8, s5, s8
	s_lshr_b32 s9, s8, 1
	s_add_i32 s8, s8, s9
	s_mul_i32 s7, s7, 5
	s_add_i32 s7, s7, s8
	s_lshl_b32 s7, s7, 11
	s_add_i32 s10, s7, s6
	s_sub_i32 s8, 2048, s6
	s_min_u32 s8, s8, 24
	s_add_i32 s11, s10, s8
	s_cmp_eq_u32 s8, 24
	s_cbranch_scc1 .Lp14_norange
	s_sub_i32 s13, 24, s8
	s_add_i32 s5, s5, 1
	s_mul_i32 s7, s5, 11
	s_lshr_b32 s7, s7, 5
	s_mul_i32 s9, s7, 3
	s_sub_i32 s9, s5, s9
	s_lshr_b32 s6, s9, 1
	s_add_i32 s9, s9, s6
	s_mul_i32 s7, s7, 5
	s_add_i32 s7, s7, s9
	s_lshl_b32 s12, s7, 11
	s_add_i32 s13, s12, s13
.Lp14_norange:
	v_mov_b32_e32 v121, s10
	v_mov_b32_e32 v122, s11
	v_mov_b32_e32 v123, s12
	v_mov_b32_e32 v124, s13
	s_mov_b32 s1, 0
	s_nop 0
	v_writelane_b32 v254, s1, 18
	s_cmp_lt_u32 s2, 128
	s_cbranch_scc1 .Lp14_resume
	s_and_saveexec_b64 s[0:1], s[84:85]
	s_cbranch_execz .Lp14_w1
	buffer_wbl2 sc1
	s_waitcnt vmcnt(0)
	s_add_u32 s6, s34, 0x321e100
	s_addc_u32 s7, s35, 0
	v_mov_b32_e32 v0, 0
	v_mov_b32_e32 v1, 1
	global_atomic_add v0, v1, s[6:7]
	s_mov_b32 s8, 0
.Lp14_spin:
	global_load_dword v2, v0, s[6:7] sc1
	s_waitcnt vmcnt(0)
	v_readfirstlane_b32 s9, v2
	s_nop 3
	s_cmp_ge_u32 s9, 0x100
	s_cbranch_scc1 .Lp14_spun
	s_sleep 2
	s_add_i32 s8, s8, 1
	s_cmp_lt_u32 s8, 0x800
	s_cbranch_scc1 .Lp14_spin
.Lp14_spun:
	buffer_inv sc1
	s_waitcnt vmcnt(0)
.Lp14_w1:
	s_or_b64 exec, exec, s[0:1]
	s_barrier
	v_readfirstlane_b32 s0, v121
	s_nop 3
	s_cmp_eq_u32 s0, -1
	s_cbranch_scc1 .Lp14_resume
	s_mov_b32 s1, 1
	s_nop 0
	v_writelane_b32 v254, s1, 18
	v_mov_b32_e32 v148, v121
	v_mov_b32_e32 v186, v122
	v_mov_b32_e32 v149, 0
	s_branch .Lseam3_entry
.Lseam3_ret:
	s_cmp_eq_u32 s0, 2
	s_cbranch_scc1 .Lp14_retclr
	v_readfirstlane_b32 s1, v123
	s_nop 3
	s_cmp_eq_u32 s1, -1
	s_cbranch_scc1 .Lp14_retclr
	s_waitcnt vmcnt(0)
	s_mov_b32 s1, 2
	s_nop 0
	v_writelane_b32 v254, s1, 18
	v_mov_b32_e32 v148, v123
	v_mov_b32_e32 v186, v124
	v_mov_b32_e32 v149, 0
	s_branch .Lseam3_entry
.Lp14_retclr:
	s_mov_b32 s1, 0
	s_nop 0
	v_writelane_b32 v254, s1, 18
.Lp14_resume:
	s_waitcnt vmcnt(0) lgkmcnt(0)
	s_barrier
	s_and_saveexec_b64 s[0:1], s[84:85]
	s_cbranch_execz .LBB0_1208
	s_add_i32 s2, 0, 0x20000
	v_mov_b32_e32 v0, s2
	s_waitcnt vmcnt(0) expcnt(0) lgkmcnt(0)
	ds_read_b32 v2, v0
	s_add_i32 s2, 0, 0x20004
	v_mov_b32_e32 v0, s2
	ds_read_b32 v0, v0
	s_waitcnt lgkmcnt(1)
	v_cmp_ne_u32_e32 vcc, 0, v2
	s_cbranch_vccnz .LBB0_1172
	s_add_u32 s2, s34, 0x321e200
	s_addc_u32 s3, s35, 0
	s_add_u32 s6, s34, 0x321e400
	s_addc_u32 s7, s35, 0
	s_add_u32 s8, s34, 0x321e500
	s_addc_u32 s9, s35, 0
	s_add_u32 s10, s34, 0x321e600
	s_addc_u32 s11, s35, 0
	s_add_u32 s12, s34, 0x321e700
	s_addc_u32 s13, s35, 0
	s_add_u32 s14, s34, 0x321e800
	s_addc_u32 s15, s35, 0
	s_add_u32 s16, s34, 0x321e900
	s_addc_u32 s17, s35, 0
	s_add_u32 s18, s34, 0x321ea00
	s_addc_u32 s19, s35, 0
	s_add_u32 s20, s34, 0x321eb00
	s_addc_u32 s21, s35, 0
	s_add_u32 s22, s34, 0x321ec00
	s_addc_u32 s23, s35, 0
	s_add_u32 s24, s34, 0x321ed00
	s_addc_u32 s25, s35, 0
	s_add_u32 s26, s34, 0x321ee00
	s_addc_u32 s27, s35, 0
	s_add_u32 s38, s34, 0x321ef00
	s_addc_u32 s39, s35, 0
	s_add_u32 s40, s34, 0x321f000
	s_addc_u32 s41, s35, 0
	s_add_u32 s42, s34, 0x321f100
	s_addc_u32 s43, s35, 0
	s_add_u32 s44, s34, 0x321f200
	s_addc_u32 s45, s35, 0
	s_mul_i32 s4, s69, s95
	s_add_u32 s46, s34, 0x321f300
	s_mul_i32 s4, s4, s68
	s_addc_u32 s47, s35, 0
	s_mov_b32 s5, 1
	v_mov_b32_e32 v16, 0
	s_branch .LBB0_1160

.Lp15_main:
	s_mov_b32 s1, 0
	v_mov_b32_e32 v148, v120
	v_add_u32_e32 v186, 8, v120
.Lp15_go:
	s_nop 0
	v_writelane_b32 v254, s1, 18
	v_mov_b32_e32 v149, 0
.Lseam3_entry:
	s_add_u32 s0, s36, 0x2000
	s_addc_u32 s1, s37, 0
	global_load_dwordx4 v[0:3], v150, s[0:1]
	global_load_dwordx4 v[4:7], v152, s[0:1]
	global_load_dwordx4 v[8:11], v154, s[0:1]
	global_load_dwordx4 v[12:15], v144, s[0:1]
	v_mbcnt_hi_u32_b32 v16, -1, v167
	v_and_b32_e32 v17, 64, v16
	v_add_u32_e32 v17, 64, v17
	v_xor_b32_e32 v18, 32, v16
	v_cmp_lt_i32_e32 vcc, v18, v17
	s_mov_b64 s[4:5], 0x1000
	s_mov_b64 s[0:1], 0x15e22e00
	v_cndmask_b32_e32 v18, v16, v18, vcc
	v_lshlrev_b32_e32 v37, 2, v18
	v_xor_b32_e32 v18, 16, v16
	v_cmp_lt_i32_e32 vcc, v18, v17
	v_mov_b32_e32 v145, 0
	s_mov_b64 s[2:3], 0x2000
	v_cndmask_b32_e32 v18, v16, v18, vcc
	v_lshlrev_b32_e32 v74, 2, v18
	v_xor_b32_e32 v18, 8, v16
	v_cmp_lt_i32_e32 vcc, v18, v17
	v_mov_b32_e32 v79, -1
	s_mov_b64 s[6:7], 0
	v_cndmask_b32_e32 v18, v16, v18, vcc
	v_lshlrev_b32_e32 v75, 2, v18
	v_xor_b32_e32 v18, 4, v16
	v_cmp_lt_i32_e32 vcc, v18, v17
	s_mov_b32 s11, 0xed400000
	s_movk_i32 s12, 0x1fff
	v_cndmask_b32_e32 v18, v16, v18, vcc
	v_lshlrev_b32_e32 v76, 2, v18
	v_xor_b32_e32 v18, 2, v16
	v_cmp_lt_i32_e32 vcc, v18, v17
	s_mov_b64 s[8:9], 0x3154000
	s_mov_b32 s10, 0x3a800000
	v_cndmask_b32_e32 v18, v16, v18, vcc
	v_lshlrev_b32_e32 v77, 2, v18
	v_xor_b32_e32 v18, 1, v16
	v_cmp_lt_i32_e32 vcc, v18, v17
	s_mov_b32 s13, 0x800000
	v_mov_b32_e32 v36, 0x358637bd
	v_cndmask_b32_e32 v16, v16, v18, vcc
	v_lshlrev_b32_e32 v78, 2, v16
	v_lshlrev_b64 v[16:17], 12, v[148:149]
	v_lshl_or_b32 v16, v147, 4, v16
	v_lshl_add_u64 v[16:17], s[30:31], 0, v[16:17]
	v_lshl_add_u64 v[32:33], v[16:17], 0, s[4:5]
	v_lshlrev_b64 v[16:17], 11, v[148:149]
	v_lshl_or_b32 v16, v147, 3, v16
	v_lshl_add_u64 v[16:17], s[34:35], 0, v[16:17]
	v_lshl_add_u64 v[34:35], v[16:17], 0, s[0:1]
	v_mov_b32_e32 v16, v145
	v_mov_b32_e32 v17, v145
	v_mov_b32_e32 v18, v145
	v_mov_b32_e32 v19, v145
	v_mov_b32_e32 v20, v145
	v_mov_b32_e32 v21, v145
	v_mov_b32_e32 v22, v145
	v_mov_b32_e32 v23, v145
	v_mov_b32_e32 v24, v145
	v_mov_b32_e32 v25, v145
	v_mov_b32_e32 v26, v145
	v_mov_b32_e32 v27, v145
	v_mov_b32_e32 v28, v145
	v_mov_b32_e32 v29, v145
	v_mov_b32_e32 v30, v145
	v_mov_b32_e32 v31, v145
	s_branch .LBB0_1211

.LBB0_1213:
	s_mov_b64 exec, -1
	v_readlane_b32 s0, v254, 18
	s_nop 3
	s_cmp_eq_u32 s0, 0
	s_cbranch_scc1 .Lseam3_end
	s_branch .Lseam3_ret
